# v24: v4 without the acquire invalidate after the recurrence-side counter polls (rows are first-touch and stored write-through)
# baseline (speedup 1.0000x reference)
.Lspin_done_g0:
.Lspin_join_g0:
	s_barrier
	v_mov_b32_e32 v36, v208
	s_lshl_b32 s0, s81, 1
	v_readfirstlane_b32 s6, v36
	s_ashr_i32 s7, s6, 6
	s_and_b32 s86, s0, 0x700
	s_lshl_b32 s0, s7, 5
	s_add_i32 s8, 0, 0x13c00
	v_bfe_u32 v38, v36, 4, 2
	s_add_i32 s0, s8, s0
	v_lshl_add_u32 v39, v38, 3, s0
	s_mov_b32 s0, s87
	s_mov_b32 s1, s87
	s_ashr_i32 s36, s70, 3
	v_and_b32_e32 v107, 15, v36
	s_mul_i32 s4, s7, 0x900
	v_mov_b64_e32 v[2:3], s[0:1]
	s_and_b32 s14, s7, 1
	s_lshl_b32 s0, s70, 7
	s_ashr_i32 s37, s36, 31
	v_mad_u32_u24 v0, v107, s83, v39
	s_and_b32 s0, s0, 0x380
	v_lshl_or_b32 v41, s14, 6, v107
	s_add_i32 s1, s4, 0
	s_lshl_b64 s[30:31], s[36:37], 13
	s_barrier
	ds_write_b64 v0, v[2:3]
	ds_write_b64 v0, v[2:3] offset:4352
	ds_write_b64 v0, v[2:3] offset:8704
	ds_write_b64 v0, v[2:3] offset:13056
	ds_write_b64 v0, v[2:3] offset:17408
	ds_write_b64 v0, v[2:3] offset:21760
	ds_write_b64 v0, v[2:3] offset:26112
	ds_write_b64 v0, v[2:3] offset:30464
	v_or_b32_e32 v0, s0, v41
	s_add_i32 s15, s1, 0x1d000
	s_lshl_b32 s0, s0, 1
	s_add_u32 s4, s38, s0
	s_addc_u32 s5, s39, 0
	s_ashr_i32 s16, s6, 7
	v_ashrrev_i32_e32 v24, 4, v36
	s_lshl_b32 s93, s16, 4
	v_bfe_u32 v42, v36, 2, 4
	v_lshlrev_b32_e32 v0, 2, v0
	v_lshlrev_b32_e32 v32, 4, v36
	v_ashrrev_i32_e32 v25, 31, v24
	v_add_u32_e32 v12, 0x200, v36
	v_or_b32_e32 v28, s93, v42
	global_load_dword v108, v0, s[52:53]
	global_load_dword v109, v0, s[52:53] offset:64
	global_load_dword v110, v0, s[52:53] offset:128
	global_load_dword v111, v0, s[52:53] offset:192
	v_and_b32_e32 v96, 0xf0, v32
	v_lshl_add_u64 v[0:1], s[30:31], 0, v[24:25]
	v_ashrrev_i32_e32 v26, 4, v12
	v_ashrrev_i32_e32 v29, 31, v28
	v_lshl_add_u64 v[8:9], s[4:5], 0, v[96:97]
	v_lshlrev_b64 v[0:1], 13, v[0:1]
	v_ashrrev_i32_e32 v27, 31, v26
	v_lshl_add_u64 v[30:31], s[30:31], 0, v[28:29]
	v_lshl_add_u64 v[10:11], v[8:9], 0, v[0:1]
	v_lshl_add_u64 v[12:13], s[30:31], 0, v[26:27]
	v_lshlrev_b64 v[30:31], 13, v[30:31]
	s_mov_b32 s1, s87
	global_load_dwordx4 v[0:3], v[10:11], off
	global_load_dwordx4 v[4:7], v[10:11], off offset:2048
	v_add_co_u32_e32 v10, vcc, s84, v10
	v_lshlrev_b64 v[12:13], 13, v[12:13]
	v_lshl_add_u64 v[30:31], s[38:39], 0, v[30:31]
	v_addc_co_u32_e32 v11, vcc, 0, v11, vcc
	v_lshl_add_u64 v[16:17], v[8:9], 0, v[12:13]
	v_lshl_add_u64 v[30:31], v[30:31], 0, s[0:1]
	s_lshl_b32 s56, s14, 7
	s_mov_b32 s57, s87
	v_add_co_u32_e32 v20, vcc, s84, v16
	v_lshl_add_u64 v[30:31], v[30:31], 0, s[56:57]
	v_and_b32_e32 v32, 48, v32
	v_mov_b32_e32 v33, v97
	v_addc_co_u32_e32 v21, vcc, 0, v17, vcc
	v_lshl_add_u64 v[30:31], v[30:31], 0, v[32:33]
	v_lshl_add_u64 v[34:35], v[30:31], 0, s[58:59]
	v_add_co_u32_e32 v30, vcc, s84, v30
	global_load_dwordx4 v[8:11], v[10:11], off
	s_nop 0
	global_load_dwordx4 v[12:15], v[16:17], off
	v_addc_co_u32_e32 v31, vcc, 0, v31, vcc
	global_load_dwordx4 v[16:19], v[16:17], off offset:2048
	s_nop 0
	global_load_dwordx4 v[20:23], v[20:21], off
	s_nop 0
	global_load_dwordx4 v[68:71], v[30:31], off offset:2048
	global_load_dwordx4 v[56:59], v[34:35], off offset:64
	s_and_b32 s0, s6, 0x3fffff80
	v_and_b32_e32 v37, 0x7f, v36
	s_add_i32 s1, 0, 0x1c400
	s_lshl_b32 s0, s0, 2
	s_add_i32 s0, s1, s0
	v_lshlrev_b32_e32 v33, 2, v37
	v_add_u32_e32 v30, 0, v96
	v_add_u32_e32 v31, s85, v96
	v_add_u32_e32 v96, s0, v33
	s_lshl_b32 s0, s16, 5
	s_add_i32 s0, s0, 0
	v_mul_u32_u24_e32 v34, 0x48, v37
	s_cmpk_lt_u32 s6, 0x80
	v_and_b32_e32 v115, 48, v36
	v_add_u32_e32 v112, s1, v33
	v_lshl_add_u32 v114, v34, 1, s0
	s_cselect_b64 s[0:1], -1, 0
	v_mov_b32_e32 v44, s8
	v_add_u32_e32 v45, s8, v115
	s_lshl_b32 s8, s16, 6
	s_add_i32 s8, s8, 0
	s_add_i32 s92, 0, 0x1cc00
	s_andn2_b32 s6, s6, 63
	v_mul_lo_u32 v48, v24, s83
	s_add_i32 s8, s8, 0x1ce00
	s_lshl_b32 s9, s14, 8
	v_add_u32_e32 v118, s92, v33
	s_add_i32 s92, s92, s6
	v_add_u32_e32 v119, v30, v48
	v_add_u32_e32 v120, v31, v48
	v_mul_lo_u32 v48, v26, s83
	s_mul_i32 s6, s16, 0x880
	s_lshl_b32 s17, s14, 1
	s_add_i32 s91, s8, s9
	s_ashr_i32 vcc_lo, s93, 31
	s_lshl_b32 s57, s7, 4
	v_add_u32_e32 v121, v30, v48
	v_or_b32_e32 v30, s6, v37
	s_addk_i32 s6, 0x110
	v_lshlrev_b32_e32 v30, 1, v30
	s_cmp_gt_i32 s16, 0
	v_add_u32_e32 v123, 0, v30
	v_add_u32_e32 v124, s85, v30
	v_add_u32_e32 v30, s6, v37
	s_cselect_b64 s[6:7], -1, 0
	s_cmp_gt_i32 s16, 1
	v_add_u32_e32 v117, s8, v115
	s_cselect_b64 s[8:9], -1, 0
	s_cmp_gt_i32 s16, 2
	s_cselect_b64 s[10:11], -1, 0
	s_cmp_gt_i32 s16, 3
	v_lshlrev_b32_e32 v113, 2, v38
	s_cselect_b64 s[12:13], -1, 0
	s_cmp_le_i32 s17, s16
	v_or_b32_e32 v36, s93, v113
	v_lshl_add_u32 v126, v30, 1, s85
	s_cselect_b64 s[34:35], -1, 0
	v_lshl_or_b32 v30, s14, 5, v107
	s_cmp_lt_i32 s17, s16
	v_add_u32_e32 v116, 0, v115
	v_mul_u32_u24_e32 v33, 0x90, v42
	v_add_u32_e32 v122, v31, v48
	v_or_b32_e32 v31, 1, v36
	v_or_b32_e32 v49, 2, v36
	v_or_b32_e32 v50, 3, v36
	s_cselect_b64 s[96:97], -1, 0
	v_or_b32_e32 v51, 16, v30
	v_mul_u32_u24_e32 v141, 0x90, v107
	s_mov_b32 s14, 0xd000
	s_add_u32 s30, s93, s30
	v_lshl_add_u32 v46, v107, 1, s15
	v_mul_u32_u24_e32 v37, 0x110, v30
	v_mul_lo_u32 v48, v36, s88
	v_add3_u32 v140, s15, v33, v32
	v_add3_u32 v142, v116, v141, s14
	v_lshl_add_u32 v33, v30, 1, s89
	v_cmp_gt_i32_e64 s[14:15], v30, v36
	v_cmp_gt_i32_e64 s[16:17], v30, v31
	v_cmp_gt_i32_e64 s[18:19], v30, v49
	v_cmp_gt_i32_e64 s[20:21], v30, v50
	v_lshlrev_b32_e32 v30, 1, v51
	s_addc_u32 s31, vcc_lo, s31
	v_add3_u32 v143, s89, v48, v30
	v_cmp_gt_i32_e64 s[24:25], v51, v31
	v_or_b32_e32 v30, s30, v42
	v_mov_b32_e32 v31, s31
	s_lshl_b64 s[30:31], s[36:37], 26
	v_lshlrev_b64 v[28:29], 13, v[28:29]
	v_lshl_add_u64 v[28:29], s[30:31], 0, v[28:29]
	v_or3_b32 v28, v28, s56, v32
	v_lshlrev_b64 v[24:25], 13, v[24:25]
	v_lshl_add_u64 v[100:101], s[74:75], 0, v[28:29]
	v_lshl_add_u64 v[24:25], s[30:31], 0, v[24:25]
	v_lshlrev_b32_e32 v28, 4, v107
	v_or_b32_e32 v24, v24, v28
	v_lshl_add_u64 v[102:103], s[74:75], 0, v[24:25]
	v_lshlrev_b64 v[24:25], 13, v[26:27]
	v_or_b32_e32 v34, s93, v107
	v_or_b32_e32 v47, s57, v107
	v_lshl_add_u64 v[24:25], s[30:31], 0, v[24:25]
	v_mul_lo_u32 v35, v34, s83
	v_mul_lo_u32 v34, v34, s88
	v_mad_u32_u24 v43, v41, s88, 0
	v_mad_u32_u24 v44, v41, s83, v44
	v_or_b32_e32 v41, 16, v41
	v_mul_lo_u32 v47, v47, s88
	v_lshlrev_b64 v[30:31], 11, v[30:31]
	v_or_b32_e32 v24, v24, v28
	v_mul_u32_u24_e32 v40, 0x110, v107
	v_add_u32_e32 v35, 0, v35
	v_add_u32_e32 v34, s89, v34
	v_add_u32_e32 v47, 0, v47
	v_mul_u32_u24_e32 v52, 0x90, v41
	v_mul_u32_u24_e32 v41, 0x110, v41
	v_mul_u32_u24_e32 v38, 0x240, v38
	v_or3_b32 v30, v30, s56, v32
	v_lshl_add_u64 v[104:105], s[74:75], 0, v[24:25]
	v_mov_b32_e32 v24, 0
	s_waitcnt vmcnt(1)
	v_mov_b64_e32 v[60:61], v[68:69]
	s_waitcnt vmcnt(0)
	v_mov_b64_e32 v[66:67], v[58:59]
	s_movk_i32 s71, 0x7f
	v_cmp_eq_u32_e64 s[4:5], 0, v107
	v_add_u32_e32 v125, 0x110, v124
	v_add_u32_e32 v127, 0x330, v124
	v_add_u32_e32 v128, 0x440, v124
	v_add_u32_e32 v129, 0x550, v124
	v_add_u32_e32 v130, 0x660, v124
	v_add_u32_e32 v131, 0x770, v124
	v_add_u32_e32 v132, 0x880, v124
	v_add_u32_e32 v133, 0x990, v124
	v_add_u32_e32 v134, 0xaa0, v124
	v_add_u32_e32 v135, 0xbb0, v124
	v_add_u32_e32 v136, 0xcc0, v124
	v_add_u32_e32 v137, 0xdd0, v124
	v_add_u32_e32 v138, 0xee0, v124
	v_add_u32_e32 v139, 0xff0, v124
	v_cmp_gt_i32_e64 s[22:23], v51, v36
	v_add_u32_e32 v144, 0x90, v143
	v_cmp_gt_i32_e64 s[26:27], v51, v49
	v_add_u32_e32 v145, 0x120, v143
	v_cmp_gt_i32_e64 s[28:29], v51, v50
	v_add_u32_e32 v146, 0x1b0, v143
	v_lshl_add_u64 v[98:99], s[74:75], 0, v[30:31]
	v_add_u32_e32 v147, v33, v48
	v_add_u32_e32 v148, v34, v115
	v_add_u32_e32 v149, v43, v115
	v_add_u32_e32 v150, v44, v115
	v_add_u32_e32 v151, v116, v52
	v_add_u32_e32 v152, v45, v41
	v_add_u32_e32 v153, v46, v38
	v_add_u32_e32 v154, v47, v115
	v_add_u32_e32 v155, v39, v40
	v_add_u32_e32 v156, v35, v115
	v_add_u32_e32 v157, v116, v37
	v_mov_b32_e32 v25, v24
	v_mov_b32_e32 v26, v24
	v_mov_b32_e32 v27, v24
	v_mov_b32_e32 v32, v24
	v_mov_b32_e32 v33, v24
	v_mov_b32_e32 v34, v24
	v_mov_b32_e32 v35, v24
	v_mov_b32_e32 v40, v24
	v_mov_b32_e32 v41, v24
	v_mov_b32_e32 v42, v24
	v_mov_b32_e32 v43, v24
	v_mov_b32_e32 v44, v24
	v_mov_b32_e32 v45, v24
	v_mov_b32_e32 v46, v24
	v_mov_b32_e32 v47, v24
	v_mov_b32_e32 v28, v24
	v_mov_b32_e32 v29, v24
	v_mov_b32_e32 v30, v24
	v_mov_b32_e32 v31, v24
	v_mov_b32_e32 v36, v24
	v_mov_b32_e32 v37, v24
	v_mov_b32_e32 v38, v24
	v_mov_b32_e32 v39, v24
	v_mov_b32_e32 v48, v24
	v_mov_b32_e32 v49, v24
	v_mov_b32_e32 v50, v24
	v_mov_b32_e32 v51, v24
	v_mov_b32_e32 v52, v24
	v_mov_b32_e32 v53, v24
	v_mov_b32_e32 v54, v24
	v_mov_b32_e32 v55, v24
	v_mov_b64_e32 v[62:63], v[70:71]
	v_mov_b64_e32 v[64:65], v[56:57]
	s_branch .LBB0_472

.Lspin_done_gn:
.Lspin_join_gn:
	s_barrier
